# barrier leaders release their XCD before issuing their own cache invalidate (every workgroup invalidates for itself)
# speedup vs baseline: 1.0022x; 1.0022x over previous
; __device__ __forceinline__ unsigned xb_ld(unsigned* p)              { return __hip_atomic_load(p, __ATOMIC_RELAXED, __HIP_MEMORY_SCOPE_AGENT); }
; __device__ __forceinline__ unsigned xb_add(unsigned* p, unsigned v) { return __hip_atomic_fetch_add(p, v, __ATOMIC_RELAXED, __HIP_MEMORY_SCOPE_AGENT); }
; #define XB_SPIN(cond, bar) do { unsigned _sp = 0; while (cond) { __builtin_amdgcn_s_sleep(1); \
;     if ((++_sp & 255u) == 0u) { if (xb_ld(&(bar)[XB_TMO])) break; if (_sp > XB_SPIN_CAP) { atomicAdd(&(bar)[XB_TMO], 1u); break; } } } } while (0)
; __device__ __forceinline__ void xcd_barrier(const XcdBarrier& b) {
;     ...
;             __builtin_amdgcn_fence(__ATOMIC_RELEASE, "agent");
;             asm volatile("s_waitcnt vmcnt(0)" ::: "memory");
;             const unsigned og = xb_add(&bar[XB_TOP], 1u);
;             const unsigned tg = og / nx;
;             if (og + 1u == (tg + 1u) * nx) xb_add(&bar[XB_TOPGEN], 1u);
;             else XB_SPIN(xb_ld(&bar[XB_TOPGEN]) == tg, bar);
;             __builtin_amdgcn_fence(__ATOMIC_ACQUIRE, "agent");
;             xb_add(&bar[XB_XGEN(b.x)], 1u);
;             asm volatile("s_waitcnt vmcnt(0)" ::: "memory");
.LBB0_137:
	s_or_b64 exec, exec, s[2:3]
	s_waitcnt vmcnt(0)
	global_atomic_add v[196:197], v241, off
	buffer_inv sc1
	s_waitcnt vmcnt(0)

; __device__ __forceinline__ unsigned xb_ld(unsigned* p)              { return __hip_atomic_load(p, __ATOMIC_RELAXED, __HIP_MEMORY_SCOPE_AGENT); }
; __device__ __forceinline__ unsigned xb_add(unsigned* p, unsigned v) { return __hip_atomic_fetch_add(p, v, __ATOMIC_RELAXED, __HIP_MEMORY_SCOPE_AGENT); }
; #define XB_SPIN(cond, bar) do { unsigned _sp = 0; while (cond) { __builtin_amdgcn_s_sleep(1); \
;     if ((++_sp & 255u) == 0u) { if (xb_ld(&(bar)[XB_TMO])) break; if (_sp > XB_SPIN_CAP) { atomicAdd(&(bar)[XB_TMO], 1u); break; } } } } while (0)
; __device__ __forceinline__ void xcd_barrier(const XcdBarrier& b) {
;     ...
;             __builtin_amdgcn_fence(__ATOMIC_RELEASE, "agent");
;             asm volatile("s_waitcnt vmcnt(0)" ::: "memory");
;             const unsigned og = xb_add(&bar[XB_TOP], 1u);
;             const unsigned tg = og / nx;
;             if (og + 1u == (tg + 1u) * nx) xb_add(&bar[XB_TOPGEN], 1u);
;             else XB_SPIN(xb_ld(&bar[XB_TOPGEN]) == tg, bar);
;             __builtin_amdgcn_fence(__ATOMIC_ACQUIRE, "agent");
;             xb_add(&bar[XB_XGEN(b.x)], 1u);
;             asm volatile("s_waitcnt vmcnt(0)" ::: "memory");
.LBB0_185:
	s_andn2_saveexec_b64 s[2:3], s[2:3]
	s_cbranch_execz .LBB0_203
	s_cmp_lg_u32 s101, 0
	s_cbranch_scc1 .Llb_grid_1
	s_waitcnt vmcnt(0) lgkmcnt(0)
	global_atomic_add v[196:197], v241, off
	buffer_inv sc1
	s_waitcnt vmcnt(0)
	s_branch .LBB0_203

; __device__ __forceinline__ unsigned xb_ld(unsigned* p)              { return __hip_atomic_load(p, __ATOMIC_RELAXED, __HIP_MEMORY_SCOPE_AGENT); }
; __device__ __forceinline__ unsigned xb_add(unsigned* p, unsigned v) { return __hip_atomic_fetch_add(p, v, __ATOMIC_RELAXED, __HIP_MEMORY_SCOPE_AGENT); }
; #define XB_SPIN(cond, bar) do { unsigned _sp = 0; while (cond) { __builtin_amdgcn_s_sleep(1); \
;     if ((++_sp & 255u) == 0u) { if (xb_ld(&(bar)[XB_TMO])) break; if (_sp > XB_SPIN_CAP) { atomicAdd(&(bar)[XB_TMO], 1u); break; } } } } while (0)
; __device__ __forceinline__ void xcd_barrier(const XcdBarrier& b) {
;     ...
;             __builtin_amdgcn_fence(__ATOMIC_RELEASE, "agent");
;             asm volatile("s_waitcnt vmcnt(0)" ::: "memory");
;             const unsigned og = xb_add(&bar[XB_TOP], 1u);
;             const unsigned tg = og / nx;
;             if (og + 1u == (tg + 1u) * nx) xb_add(&bar[XB_TOPGEN], 1u);
;             else XB_SPIN(xb_ld(&bar[XB_TOPGEN]) == tg, bar);
;             __builtin_amdgcn_fence(__ATOMIC_ACQUIRE, "agent");
;             xb_add(&bar[XB_XGEN(b.x)], 1u);
;             asm volatile("s_waitcnt vmcnt(0)" ::: "memory");
.LBB0_202:
	s_or_b64 exec, exec, s[4:5]
	s_waitcnt vmcnt(0)
	global_atomic_add v[196:197], v241, off
	buffer_inv sc1
	s_waitcnt vmcnt(0)
